# plus A2: softmax offset pre-loaded into QK accumulators (C operand) via v_mov_b64 during LDS latency, 64 per-element adds removed; running max starts at -200
# speedup vs baseline: 1.0170x; 1.0067x over previous
; __device__ __forceinline__ int lane_id_v() { int l; asm volatile("v_mbcnt_lo_u32_b32 %0, -1, 0\n\tv_mbcnt_hi_u32_b32 %0, -1, %0" : "=v"(l)); return l; }
; __device__ __forceinline__ int v_st(int k, int c) { const int kk = (k & ~0xC) | ((k & 4) << 1) | ((k & 8) >> 1); return ((kk >> 3) * 4 + (c >> 5)) * 512 + ((kk & 7) * 32 + (c & 31)) * 2; }
; __device__ __forceinline__ int v_rd_base(int lane) { return ((lane & 3) << 3) | (((lane >> 2) & 3) << 6) | (((lane >> 4) & 1) << 5) | (((lane >> 5) & 1) << 8); }
; #define SLOAD2(k0) do { vs0 = *reinterpret_cast<const bf16x8*>(&Vh[(long)((k0) + sr) * ldv + sc]); vs1 = *reinterpret_cast<const bf16x8*>(&Vh[(long)((k0) + 32 + sr) * ldv + sc]); \
;     ks0 = *reinterpret_cast<const bf16x8*>(&Kh[(long)((k0) + sr) * ldk + sc]); ks1 = *reinterpret_cast<const bf16x8*>(&Kh[(long)((k0) + 32 + sr) * ldk + sc]); } while (0)
; __device__ __forceinline__ void attn_unit_A2(const bf16_t* __restrict__ Qb, int ldq, const bf16_t* __restrict__ Kh, int ldk, const bf16_t* __restrict__ Vh, int ldv, int nkeys, int q0, ...
;   constexpr int ROWB = 256, SHM_K = 64 * ROWB;
;   int tid_ = wave0 * 64 + lane_id_v();
;   const int tid = tid_, wid = tid >> 6, lane = tid & 63, r32 = lane & 31, hi = lane >> 5;
;   char* V_lds = lds; char* K_lds = lds + LDS_K_OFF;
;   float* ws = (float*)(lds + LDS_WS_OFF) + wid * 64; float* sl0 = ws; float* sl1 = ws + 32;
;   float* tbl_l = (float*)(lds + LDS_TBL_OFF);
;   char* qls = lds + LDS_Q_OFF + wid * 8192 + lane * 16;
;   __syncthreads();
;   for (int i = tid; i < TBLN; i += 512) tbl_l[i] = tblg[i];
;   { const bf16_t* Qw = Qb + (long)(wid * QBLK + r32) * ldq + hi * 8;
; #pragma unroll
;     for (int i = 0; i < 8; ++i) *reinterpret_cast<bf16x8*>(qls + i * 1024) = *reinterpret_cast<const bf16x8*>(Qw + i * 16); }
;   float m0 = -1e30f, m1 = -1e30f, l0 = 0.f, l1 = 0.f; f32x16 oa[4] = {}, ob[4] = {};
;   const int sr = tid >> 4, sc = (tid & 15) * 8, vst0 = v_st(sr, sc), vst1 = v_st(32 + sr, sc);
;   const int vb0 = (int)(uintptr_t)V_lds + v_rd_base(lane);
;   const int qlane = q0 + wid * QBLK + r32;
;   bf16x8 vs0, vs1, ks0, ks1;
;     ...
;   const int NT = nkeys / KVBLK;
;   const int kbA = (int)(uintptr_t)K_lds + r32 * 256 + (((r32 & 15) << 4) ^ (hi << 4)), qaA = (int)(uintptr_t)qls;
;   SLOAD2(0); asm volatile("s_waitcnt vmcnt(0)" ::: "memory"); SWRITE2(0); __syncthreads();
.LBB0_334:
	s_or_b64 exec, exec, s[4:5]
	s_lshl_b32 s4, s57, 8
	s_and_b32 s7, s4, 0x2000
	s_lshl_b32 s4, s59, 3
	s_ashr_i32 s23, s59, 3
	s_and_b32 s4, s4, 32
	s_add_i32 s4, s4, s23
	s_lshl_b32 s6, s20, 8
	s_lshl_b32 s20, s4, 8
	s_ashr_i32 s21, s20, 31
	s_mul_i32 s4, s4, 0x280000
	s_mul_hi_i32 s5, s20, 0x2800
	s_add_u32 s4, s24, s4
	s_addc_u32 s5, s25, s5
	s_lshl_b32 s10, s22, 7
	s_lshl_b32 s8, s22, 8
	v_ashrrev_i32_e32 v3, 6, v2
	s_add_u32 s4, s4, s8
	s_addc_u32 s5, s5, 0
	v_and_b32_e32 v46, 31, v6
	v_lshlrev_b32_e32 v196, 5, v3
	v_or_b32_e32 v0, v196, v46
	v_mov_b64_e32 v[4:5], s[4:5]
	v_mad_i64_i32 v[4:5], s[4:5], v0, s55, v[4:5]
	v_and_b32_e32 v9, 63, v6
	s_add_u32 s4, s26, s8
	v_lshrrev_b32_e32 v47, 5, v9
	s_addc_u32 s5, s27, 0
	v_lshlrev_b32_e32 v0, 4, v47
	s_add_u32 s8, s45, s8
	v_lshl_add_u64 v[4:5], v[4:5], 0, v[0:1]
	s_addc_u32 s9, s46, 0
	v_lshlrev_b32_e32 v49, 3, v6
	global_load_dwordx4 v[10:13], v[4:5], off
	global_load_dwordx4 v[14:17], v[4:5], off offset:32
	global_load_dwordx4 v[18:21], v[4:5], off offset:64
	global_load_dwordx4 v[22:25], v[4:5], off offset:96
	global_load_dwordx4 v[26:29], v[4:5], off offset:128
	global_load_dwordx4 v[30:33], v[4:5], off offset:160
	global_load_dwordx4 v[34:37], v[4:5], off offset:192
	global_load_dwordx4 v[38:41], v[4:5], off offset:224
	v_ashrrev_i32_e32 v48, 4, v2
	v_and_b32_e32 v4, 0x78, v49
	v_mov_b64_e32 v[42:43], s[8:9]
	v_lshlrev_b32_e32 v4, 1, v4
	v_add_u32_e32 v50, 32, v48
	v_mad_i64_i32 v[44:45], s[8:9], v48, s55, v[42:43]
	v_mov_b32_e32 v5, v1
	v_lshl_add_u64 v[44:45], v[44:45], 0, v[4:5]
	v_mad_i64_i32 v[42:43], s[8:9], v50, s55, v[42:43]
	global_load_dwordx4 v[176:179], v[44:45], off
	v_lshl_add_u64 v[42:43], v[42:43], 0, v[4:5]
	global_load_dwordx4 v[180:183], v[42:43], off
	v_mov_b64_e32 v[42:43], s[4:5]
	v_mad_i64_i32 v[44:45], s[4:5], v48, s55, v[42:43]
	v_lshl_add_u64 v[44:45], v[44:45], 0, v[4:5]
	global_load_dwordx4 v[184:187], v[44:45], off
	v_mad_i64_i32 v[42:43], s[4:5], v50, s55, v[42:43]
	v_lshl_add_u64 v[42:43], v[42:43], 0, v[4:5]
	global_load_dwordx4 v[188:191], v[42:43], off
	s_waitcnt vmcnt(13)
	v_mul_f32_e32 v197, 0x3fb8aa3b, v7
	s_waitcnt vmcnt(12)
	v_mul_f32_e32 v207, 0x3fb8aa3b, v8
	v_lshlrev_b32_e32 v3, 13, v3
	v_lshlrev_b32_e32 v7, 4, v9
	v_and_b32_e32 v8, 0xfffff0, v48
	v_lshlrev_b32_e32 v42, 1, v48
	v_readlane_b32 s4, v254, 58
	v_lshrrev_b32_e32 v43, 1, v48
	v_bfe_u32 v44, v49, 5, 2
	v_add3_u32 v208, s4, v3, v7
	v_and_or_b32 v3, v48, 8, v8
	v_and_b32_e32 v45, 3, v48
	v_lshrrev_b32_e32 v3, 1, v3
	v_and_or_b32 v8, v48, 4, v45
	v_or_b32_e32 v3, v3, v44
	v_and_b32_e32 v5, 0x3fffffc0, v2
	v_lshlrev_b32_e32 v8, 6, v8
	v_and_b32_e32 v42, 48, v4
	v_lshlrev_b32_e32 v3, 9, v3
	s_add_i32 s37, 0, 0x14000
	v_or3_b32 v209, v3, v8, v42
	v_lshl_add_u32 v201, v5, 2, s37
	v_and_b32_e32 v3, 0xfffff0, v50
	v_lshlrev_b32_e32 v5, 1, v50
	v_and_or_b32 v3, v50, 8, v3
	v_lshrrev_b32_e32 v3, 1, v3
	v_or_b32_e32 v3, v3, v44
	v_lshlrev_b32_e32 v3, 9, v3
	v_or3_b32 v210, v3, v8, v42
	v_and_b32_e32 v2, 0xf0, v2
	s_add_i32 s44, 0, 0x8000
	v_and_b32_e32 v8, 0xc0, v7
	v_lshlrev_b32_e32 v7, 1, v9
	s_cmp_lg_u32 s44, -1
	s_cselect_b32 s4, s44, 0
	s_add_i32 s60, s20, 0x4ff
	s_waitcnt vmcnt(11)
	ds_write_b128 v208, v[10:13]
	s_waitcnt vmcnt(10)
	ds_write_b128 v208, v[14:17] offset:1024
	s_waitcnt vmcnt(9)
	ds_write_b128 v208, v[18:21] offset:2048
	s_waitcnt vmcnt(8)
	ds_write_b128 v208, v[22:25] offset:3072
	s_waitcnt vmcnt(7)
	ds_write_b128 v208, v[26:29] offset:4096
	s_waitcnt vmcnt(6)
	ds_write_b128 v208, v[30:33] offset:5120
	s_waitcnt vmcnt(5)
	ds_write_b128 v208, v[34:37] offset:6144
	s_waitcnt vmcnt(4)
	ds_write_b128 v208, v[38:41] offset:7168
	v_add_u32_e32 v12, 0, v209
	s_waitcnt vmcnt(0)
	v_and_b32_e32 v11, 15, v6
	v_bitop3_b32 v6, v47, v6, 15 bitop3:0x78
	v_and_b32_e32 v10, 32, v7
	v_lshlrev_b32_e32 v7, 8, v46
	v_lshlrev_b32_e32 v6, 4, v6
	v_lshlrev_b32_e32 v3, 3, v9
	v_add3_u32 v211, v7, s4, v6
	v_mad_i64_i32 v[6:7], s[4:5], v48, s55, 0
	s_waitcnt vmcnt(3)
	ds_write_b128 v12, v[176:179]
	v_add_u32_e32 v12, 0, v210
	s_waitcnt vmcnt(2)
	ds_write_b128 v12, v[180:183]
	v_lshlrev_b32_e32 v12, 8, v48
	v_bitop3_b32 v212, v4, v12, v2 bitop3:0xde
	v_add_u32_e32 v12, 0, v212
	s_cmp_lg_u32 0, -1
	s_waitcnt vmcnt(1)
	ds_write_b128 v12, v[184:187] offset:32768
	v_lshlrev_b32_e32 v12, 8, v50
	v_bitop3_b32 v213, v12, v4, v2 bitop3:0xf6
	v_and_b32_e32 v5, 24, v3
	v_add_u32_e32 v2, 0, v213
	s_cselect_b32 s4, 0, 0
	s_lshl_b32 s8, s23, 8
	v_and_b32_e32 v3, 0x100, v3
	s_waitcnt vmcnt(0)
; template <int M>
; __device__ __forceinline__ void qkt_map_roll(f32x16& p0, f32x16& p1, int kb, int qa) {
;   p0 = f32x16{}; p1 = f32x16{};
;   const int a0 = kb ^ ((M << 7) | (0 << 5)); const bf16x8 x0 = lds_rd128<0>(a0), y0 = lds_rd128<8192>(a0); const bf16x8 z0 = (M == 0) ? lds_rd128<0>(qa) : lds_rd128<4096>(qa);
;   const int a1 = kb ^ ((M << 7) | (1 << 5)); const bf16x8 x1 = lds_rd128<0>(a1), y1 = lds_rd128<8192>(a1); const bf16x8 z1 = (M == 0) ? lds_rd128<1024>(qa) : lds_rd128<5120>(qa);
;   asm volatile("s_waitcnt lgkmcnt(3)" ::: "memory"); SBAR();
;   p0 = __builtin_amdgcn_mfma_f32_32x32x16_bf16(x0, z0, p0, 0, 0, 0); p1 = __builtin_amdgcn_mfma_f32_32x32x16_bf16(y0, z0, p1, 0, 0, 0);
;   const int a2 = kb ^ ((M << 7) | (2 << 5)); const bf16x8 x2 = lds_rd128<0>(a2), y2 = lds_rd128<8192>(a2); const bf16x8 z2 = (M == 0) ? lds_rd128<2048>(qa) : lds_rd128<6144>(qa);
;   asm volatile("s_waitcnt lgkmcnt(3)" ::: "memory"); SBAR();
;   p0 = __builtin_amdgcn_mfma_f32_32x32x16_bf16(x1, z1, p0, 0, 0, 0); p1 = __builtin_amdgcn_mfma_f32_32x32x16_bf16(y1, z1, p1, 0, 0, 0);
; __device__ __forceinline__ void attn_unit_A2(const bf16_t* __restrict__ Qb, int ldq, const bf16_t* __restrict__ Kh, int ldk, const bf16_t* __restrict__ Vh, int ldv, int nkeys, int q0, ...
;     ...
;   float m0 = -1e30f, m1 = -1e30f, l0 = 0.f, l1 = 0.f; f32x16 oa[4] = {}, ob[4] = {};
;   const int sr = tid >> 4, sc = (tid & 15) * 8, vst0 = v_st(sr, sc), vst1 = v_st(32 + sr, sc);
;   const int vb0 = (int)(uintptr_t)V_lds + v_rd_base(lane);
;   const int qlane = q0 + wid * QBLK + r32;
;   bf16x8 vs0, vs1, ks0, ks1;
;     ...
;   const int NT = nkeys / KVBLK;
;   const int kbA = (int)(uintptr_t)K_lds + r32 * 256 + (((r32 & 15) << 4) ^ (hi << 4)), qaA = (int)(uintptr_t)qls;
;   SLOAD2(0); asm volatile("s_waitcnt vmcnt(0)" ::: "memory"); SWRITE2(0); __syncthreads();
;   for (int j = 0; j < NT; ++j) {
;     const int b = j & 1, kt0 = j * KVBLK;
;     const int dlo_ = kt0 - q0 - 255, dhi_ = kt0 + 63 - q0;
;     float cb = 0.f; const bool nearb = !(dlo_ >= 1024) && !(dhi_ <= -1024);
;     if (dlo_ >= 1024) cb = cb_hi; else if (dhi_ <= -1024) cb = cb_lo;
;     const float* tb_ = tbl_l + (kt0 - qlane + TOFF + 4 * hi);
;     f32x16 s0, s1; bf16x8 pa0, pa1, pa2, pa3; float al0, al1;
;     const int vb = vb0 + b * (int)SHM_V;
;     qkt_map_roll<0>(s0, s1, kbA + b * SHM_K, qaA);
	ds_write_b128 v2, v[188:191] offset:32768
	v_add3_u32 v2, v8, s4, v5
	s_add_i32 s7, s7, s8
	v_add3_u32 v214, v2, v10, v3
	v_add_u32_e32 v2, s7, v196
	v_or_b32_e32 v2, v2, v46
	v_lshlrev_b32_e32 v2, 2, v2
	v_add_u32_e32 v216, v201, v0
	v_sub_u32_e32 v0, v0, v2
	v_add_u32_e32 v217, 0, v0
	v_lshlrev_b32_e32 v0, 4, v11
	v_or3_b32 v6, v6, s6, v0
	v_mov_b32_e32 v14, v1
	v_mov_b32_e32 v15, v1
	v_cmp_gt_u32_e64 s[4:5], 32, v9
	v_lshl_add_u32 v215, v46, 2, v201
	v_lshl_add_u64 v[198:199], s[18:19], 0, v[6:7]
	v_mov_b32_e32 v0, v1
	v_mov_b32_e32 v2, v1
	v_mov_b32_e32 v3, v1
	v_mov_b32_e32 v4, v1
	v_mov_b32_e32 v5, v1
	v_mov_b32_e32 v6, v1
	v_mov_b32_e32 v7, v1
	v_mov_b32_e32 v8, v1
	v_mov_b32_e32 v9, v1
	v_mov_b32_e32 v10, v1
	v_mov_b32_e32 v11, v1
	v_mov_b32_e32 v12, v1
	v_mov_b32_e32 v13, v1
	v_mov_b64_e32 v[46:47], v[14:15]
	v_mov_b64_e32 v[30:31], v[14:15]
	v_mov_b64_e32 v[78:79], v[14:15]
	v_mov_b64_e32 v[126:127], v[14:15]
	v_mov_b64_e32 v[142:143], v[14:15]
	v_mov_b64_e32 v[110:111], v[14:15]
	v_mov_b64_e32 v[62:63], v[14:15]
	v_mov_b64_e32 v[94:95], v[14:15]
	s_mov_b32 s11, 0
	s_sub_i32 s61, 0, s7
	v_mov_b32_e32 v218, 0xc3480000
	v_mov_b32_e32 v219, 0
	s_mov_b32 s62, 0
	s_mov_b32 s63, 0
	v_mov_b64_e32 v[44:45], v[12:13]
	v_mov_b64_e32 v[42:43], v[10:11]
	v_mov_b64_e32 v[40:41], v[8:9]
	v_mov_b64_e32 v[38:39], v[6:7]
	v_mov_b64_e32 v[36:37], v[4:5]
	v_mov_b64_e32 v[34:35], v[2:3]
	v_mov_b64_e32 v[32:33], v[0:1]
	v_mov_b64_e32 v[28:29], v[12:13]
	v_mov_b64_e32 v[26:27], v[10:11]
	v_mov_b64_e32 v[24:25], v[8:9]
	v_mov_b64_e32 v[22:23], v[6:7]
	v_mov_b64_e32 v[20:21], v[4:5]
	v_mov_b64_e32 v[18:19], v[2:3]
	v_mov_b64_e32 v[16:17], v[0:1]
	v_mov_b64_e32 v[76:77], v[12:13]
	v_mov_b64_e32 v[74:75], v[10:11]
	v_mov_b64_e32 v[72:73], v[8:9]
	v_mov_b64_e32 v[70:71], v[6:7]
	v_mov_b64_e32 v[68:69], v[4:5]
	v_mov_b64_e32 v[66:67], v[2:3]
	v_mov_b64_e32 v[64:65], v[0:1]
	v_mov_b64_e32 v[124:125], v[12:13]
	v_mov_b64_e32 v[122:123], v[10:11]
	v_mov_b64_e32 v[120:121], v[8:9]
	v_mov_b64_e32 v[118:119], v[6:7]
	v_mov_b64_e32 v[116:117], v[4:5]
	v_mov_b64_e32 v[114:115], v[2:3]
	v_mov_b64_e32 v[112:113], v[0:1]
	v_mov_b64_e32 v[140:141], v[12:13]
	v_mov_b64_e32 v[138:139], v[10:11]
	v_mov_b64_e32 v[136:137], v[8:9]
	v_mov_b64_e32 v[134:135], v[6:7]
	v_mov_b64_e32 v[132:133], v[4:5]
	v_mov_b64_e32 v[130:131], v[2:3]
	v_mov_b64_e32 v[128:129], v[0:1]
	v_mov_b64_e32 v[108:109], v[12:13]
	v_mov_b64_e32 v[106:107], v[10:11]
	v_mov_b64_e32 v[104:105], v[8:9]
	v_mov_b64_e32 v[102:103], v[6:7]
	v_mov_b64_e32 v[100:101], v[4:5]
	v_mov_b64_e32 v[98:99], v[2:3]
	v_mov_b64_e32 v[96:97], v[0:1]
	v_mov_b64_e32 v[60:61], v[12:13]
	v_mov_b64_e32 v[58:59], v[10:11]
	v_mov_b64_e32 v[56:57], v[8:9]
	v_mov_b64_e32 v[54:55], v[6:7]
	v_mov_b64_e32 v[52:53], v[4:5]
	v_mov_b64_e32 v[50:51], v[2:3]
	v_mov_b64_e32 v[48:49], v[0:1]
	v_mov_b64_e32 v[92:93], v[12:13]
	v_mov_b64_e32 v[90:91], v[10:11]
	v_mov_b64_e32 v[88:89], v[8:9]
	v_mov_b64_e32 v[86:87], v[6:7]
	v_mov_b64_e32 v[84:85], v[4:5]
	v_mov_b64_e32 v[82:83], v[2:3]
	v_mov_b64_e32 v[80:81], v[0:1]
	v_mov_b32_e32 v14, 0
	v_mov_b32_e32 v0, 0xc3480000
	s_waitcnt lgkmcnt(0)
	s_barrier
.LBB0_335:
	s_add_i32 s6, s61, s11
	s_cmp_lt_i32 s11, s60
	s_cselect_b64 s[8:9], -1, 0
	s_cmpk_gt_i32 s6, 0xfbc1
	s_cselect_b64 s[22:23], -1, 0
	v_cndmask_b32_e64 v227, v197, 0, s[22:23]
	v_cndmask_b32_e64 v227, v207, v227, s[8:9]
	s_and_b32 s64, s62, 0x4000
	v_add_u32_e32 v226, s64, v211
	ds_read_b128 v[2:5], v226 offset:0
	ds_read_b128 v[6:9], v226 offset:0x2000
	ds_read_b128 v[10:13], v208 offset:0
	v_xor_b32_e32 v144, 32, v226
	ds_read_b128 v[228:231], v144 offset:0
	ds_read_b128 v[232:235], v144 offset:0x2000
	ds_read_b128 v[236:239], v208 offset:0x400
	v_sub_f32_e32 v160, v227, v0
	v_mov_b32_e32 v161, v160
	v_mov_b64_e32 v[162:163], v[160:161]
	v_mov_b64_e32 v[164:165], v[160:161]
	v_mov_b64_e32 v[166:167], v[160:161]
	v_mov_b64_e32 v[168:169], v[160:161]
	v_mov_b64_e32 v[170:171], v[160:161]
	v_mov_b64_e32 v[172:173], v[160:161]
	v_mov_b64_e32 v[174:175], v[160:161]
	v_mov_b64_e32 v[144:145], v[160:161]
	v_mov_b64_e32 v[146:147], v[160:161]
	v_mov_b64_e32 v[148:149], v[160:161]
	v_mov_b64_e32 v[150:151], v[160:161]
	v_mov_b64_e32 v[152:153], v[160:161]
	v_mov_b64_e32 v[154:155], v[160:161]
	v_mov_b64_e32 v[156:157], v[160:161]
	v_mov_b64_e32 v[158:159], v[160:161]
	s_waitcnt lgkmcnt(3)
	s_and_b64 s[76:77], s[8:9], s[22:23]
	v_mfma_f32_32x32x16_bf16 v[160:175], v[2:5], v[10:13], v[160:175]
	v_mfma_f32_32x32x16_bf16 v[144:159], v[6:9], v[10:13], v[144:159]
	v_xor_b32_e32 v10, 64, v226
	ds_read_b128 v[2:5], v10 offset:0
	ds_read_b128 v[6:9], v10 offset:0x2000
	ds_read_b128 v[10:13], v208 offset:0x800
	s_waitcnt lgkmcnt(3)
	v_mfma_f32_32x32x16_bf16 v[160:175], v[228:231], v[236:239], v[160:175]
	v_xor_b32_e32 v192, 0x60, v226
	ds_read_b128 v[228:231], v192 offset:0
	v_mfma_f32_32x32x16_bf16 v[144:159], v[232:235], v[236:239], v[144:159]
	ds_read_b128 v[232:235], v192 offset:0x2000
	ds_read_b128 v[236:239], v208 offset:0xc00
	s_waitcnt lgkmcnt(3)
	v_mfma_f32_32x32x16_bf16 v[160:175], v[2:5], v[10:13], v[160:175]
	s_waitcnt lgkmcnt(0)
	v_mfma_f32_32x32x16_bf16 v[144:159], v[6:9], v[10:13], v[144:159]
	v_mfma_f32_32x32x16_bf16 v[160:175], v[228:231], v[236:239], v[160:175]
	v_mfma_f32_32x32x16_bf16 v[144:159], v[232:235], v[236:239], v[144:159]
	v_cndmask_b32_e64 v2, 0, 1, s[76:77]
	v_cmp_ne_u32_e64 s[6:7], 1, v2
	s_andn2_b64 vcc, exec, s[76:77]
	s_cbranch_vccnz .LBB0_337
; #define SBAR() __builtin_amdgcn_sched_barrier(0)
; __device__ __forceinline__ void softmax_tile(f32x16& p0, f32x16& p1, float& m, float& l, float& alpha, float cb, bf16x8& pa0, bf16x8& pa1, bf16x8& pa2, bf16x8& pa3) {
;   float mx_[4] = {p0[0], p0[1], p0[2], p0[3]};
; #pragma unroll
;   for (int r = 4; r < 16; ++r) mx_[r & 3] = fmaxf(mx_[r & 3], p0[r]);
; #pragma unroll
;   for (int r = 0; r < 16; ++r) mx_[r & 3] = fmaxf(mx_[r & 3], p1[r]);
;   float pmax = fmaxf(fmaxf(mx_[0], mx_[1]), fmaxf(mx_[2], mx_[3]));
;   { auto rr = __builtin_amdgcn_permlane32_swap(__float_as_uint(pmax), __float_as_uint(pmax), false, false);
;     pmax = fmaxf(__uint_as_float(rr[0]), __uint_as_float(rr[1])); }
;   pmax += cb;
;   float mn;
;   if (__builtin_expect(__all(pmax - m <= THR2), 1)) { mn = m; alpha = 1.f; }
;   else { mn = fmaxf(m, pmax); alpha = __builtin_amdgcn_exp2f(m - mn); m = mn; }
;   const float off = cb - mn;
; #pragma unroll
;   for (int r = 0; r < 16; ++r) p0[r] = __builtin_amdgcn_exp2f(p0[r] + off);
; #pragma unroll
;   for (int r = 0; r < 16; ++r) p1[r] = __builtin_amdgcn_exp2f(p1[r] + off);
;   float sm_[4] = {p0[0], p0[1], p0[2], p0[3]};
; #pragma unroll
;   for (int r = 4; r < 16; ++r) sm_[r & 3] += p0[r];
; #pragma unroll
;   for (int r = 0; r < 16; ++r) sm_[r & 3] += p1[r];
;   float ps = (sm_[0] + sm_[1]) + (sm_[2] + sm_[3]);
;   { auto rr = __builtin_amdgcn_permlane32_swap(__float_as_uint(ps), __float_as_uint(ps), false, false);
;     ps = __uint_as_float(rr[0]) + __uint_as_float(rr[1]); }
;   l = l * alpha + ps;
;     ...
;   PK4(p0, 0, pa0); PK4(p0, 8, pa1); PK4(p1, 0, pa2); PK4(p1, 8, pa3);
;     ...
; }
; __device__ __forceinline__ void attn_unit_A2(const bf16_t* __restrict__ Qb, int ldq, const bf16_t* __restrict__ Kh, int ldk, const bf16_t* __restrict__ Vh, int ldv, int nkeys, int q0, ...
;     ...
;     if (nearb) {
; #pragma unroll
;       for (int r = 0; r < 8; ++r) { s0[r] += tb_[(r & 3) + 8 * (r >> 2)]; s1[r] += tb_[32 + (r & 3) + 8 * (r >> 2)]; }
;       SBAR();
; #pragma unroll
;       for (int r = 8; r < 16; ++r) { s0[r] += tb_[(r & 3) + 8 * (r >> 2)]; s1[r] += tb_[32 + (r & 3) + 8 * (r >> 2)]; } }
;     SBAR();
;     softmax_tile(s0, s1, m0, l0, al0, cb, pa0, pa1, pa2, pa3);
;     RESC2(oa, sl0, al0);
	v_add_u32_e32 v15, s63, v217
	v_add_u32_e32 v223, 0x15e00, v15
	v_add_u32_e32 v234, 0x15e80, v15
	v_add_u32_e32 v235, 0x15e08, v15
	v_add_u32_e32 v236, 0x15e88, v15
	v_add_u32_e32 v237, 0x15e20, v15
	v_add_u32_e32 v238, 0x15ea0, v15
	v_add_u32_e32 v239, 0x15e28, v15
	v_add_u32_e32 v240, 0x15ea8, v15
	v_add_u32_e32 v228, 0x15e40, v15
	v_add_u32_e32 v229, 0x15ec0, v15
	v_add_u32_e32 v230, 0x15e48, v15
	v_add_u32_e32 v231, 0x15ec8, v15
	v_add_u32_e32 v232, 0x15e60, v15
	v_add_u32_e32 v224, 0x15ee0, v15
	v_add_u32_e32 v233, 0x15e68, v15
	v_add_u32_e32 v225, 0x15ee8, v15
	ds_read2_b32 v[2:3], v223 offset1:1
	ds_read2_b32 v[4:5], v234 offset1:1
	ds_read2_b32 v[6:7], v235 offset1:1
	ds_read2_b32 v[8:9], v236 offset1:1
	ds_read2_b32 v[10:11], v237 offset1:1
	ds_read2_b32 v[12:13], v238 offset1:1
	ds_read2_b32 v[192:193], v239 offset1:1
	ds_read2_b32 v[194:195], v240 offset1:1
	ds_read2_b32 v[202:203], v228 offset1:1
	ds_read2_b32 v[204:205], v229 offset1:1
	ds_read2_b32 v[220:221], v230 offset1:1
	ds_read2_b32 v[242:243], v231 offset1:1
	ds_read2_b32 v[244:245], v232 offset1:1
	ds_read2_b32 v[246:247], v233 offset1:1
	s_waitcnt lgkmcnt(9)
	v_add_f32_e32 v164, v164, v10
	v_add_f32_e32 v165, v165, v11
	v_add_f32_e32 v162, v162, v6
	v_add_f32_e32 v163, v163, v7
	ds_read2_b32 v[6:7], v225 offset1:1
	ds_read2_b32 v[10:11], v224 offset1:1
	s_waitcnt lgkmcnt(9)
	v_add_f32_e32 v166, v166, v192
	v_add_f32_e32 v167, v167, v193
	s_waitcnt lgkmcnt(2)
	v_add_f32_e32 v174, v174, v246
	v_add_f32_e32 v175, v175, v247
	v_add_f32_e32 v172, v172, v244
	v_add_f32_e32 v173, v173, v245
	v_add_f32_e32 v170, v170, v220
	v_add_f32_e32 v171, v171, v221
	v_add_f32_e32 v168, v168, v202
	v_add_f32_e32 v169, v169, v203
	v_add_f32_e32 v160, v160, v2
	v_add_f32_e32 v161, v161, v3
	v_add_f32_e32 v150, v150, v194
	v_add_f32_e32 v151, v151, v195
	v_add_f32_e32 v148, v148, v12
	v_add_f32_e32 v149, v149, v13
	v_add_f32_e32 v146, v146, v8
	v_add_f32_e32 v147, v147, v9
	s_waitcnt lgkmcnt(1)
	v_add_f32_e32 v158, v158, v6
	v_add_f32_e32 v159, v159, v7
	s_waitcnt lgkmcnt(0)
	v_add_f32_e32 v156, v156, v10
	v_add_f32_e32 v157, v157, v11
	v_add_f32_e32 v154, v154, v242
	v_add_f32_e32 v155, v155, v243
	v_add_f32_e32 v152, v152, v204
	v_add_f32_e32 v153, v153, v205
	v_add_f32_e32 v144, v144, v4
	v_add_f32_e32 v145, v145, v5
.LBB0_337:
	s_nop 6
	v_max_f32_e32 v2, v160, v164
	v_max_f32_e32 v3, v161, v165
	v_max_f32_e32 v4, v163, v167
	v_max3_f32 v5, v162, v166, v170
	v_max3_f32 v4, v4, v171, v175
	v_max3_f32 v2, v2, v168, v172
	v_max3_f32 v3, v3, v169, v173
	v_max3_f32 v5, v5, v174, v146
	v_max3_f32 v4, v4, v147, v151
	v_max3_f32 v2, v2, v144, v148
	v_max3_f32 v3, v3, v145, v149
	v_max3_f32 v5, v5, v150, v154
	v_max3_f32 v4, v4, v155, v159
	v_max3_f32 v2, v2, v152, v156
	v_max3_f32 v3, v3, v153, v157
	v_max3_f32 v4, v5, v158, v4
	v_max3_f32 v2, v2, v3, v4
	v_cmp_ge_f32_e32 vcc, s48, v2
	s_cmp_eq_u64 vcc, exec
	s_cbranch_scc0 .Lmy_A_rare0
	v_mov_b32_e32 v15, 1.0
.Lmy_A_back0:
	v_exp_f32_e32 v3, v160
	v_exp_f32_e32 v4, v161
	v_exp_f32_e32 v5, v162
	v_exp_f32_e32 v6, v163
	v_exp_f32_e32 v7, v164
	v_exp_f32_e32 v8, v165
	v_exp_f32_e32 v9, v166
	v_exp_f32_e32 v10, v167
	v_exp_f32_e32 v11, v168
	v_exp_f32_e32 v12, v169
	v_exp_f32_e32 v13, v170
	v_exp_f32_e32 v160, v171
	v_exp_f32_e32 v161, v172
	v_exp_f32_e32 v162, v173
	v_exp_f32_e32 v163, v174
	v_exp_f32_e32 v164, v175
	v_exp_f32_e32 v144, v144
	v_exp_f32_e32 v145, v145
	v_exp_f32_e32 v146, v146
	v_exp_f32_e32 v147, v147
	v_exp_f32_e32 v148, v148
	v_exp_f32_e32 v149, v149
	v_exp_f32_e32 v150, v150
	v_exp_f32_e32 v151, v151
	v_exp_f32_e32 v159, v159
	v_add_f32_e32 v2, v7, v3
	v_add_f32_e32 v165, v8, v4
	v_add_f32_e32 v166, v9, v5
	v_add_f32_e32 v167, v10, v6
	v_exp_f32_e32 v152, v152
	v_exp_f32_e32 v153, v153
	v_exp_f32_e32 v154, v154
	v_exp_f32_e32 v155, v155
	v_add_f32_e32 v2, v11, v2
	v_add_f32_e32 v165, v12, v165
	v_add_f32_e32 v166, v13, v166
	v_add_f32_e32 v167, v160, v167
	v_exp_f32_e32 v156, v156
	v_exp_f32_e32 v157, v157
	v_exp_f32_e32 v158, v158
	v_add_f32_e32 v2, v161, v2
	v_add_f32_e32 v165, v162, v165
	v_add_f32_e32 v166, v163, v166
	v_add_f32_e32 v167, v164, v167
	v_add_f32_e32 v2, v144, v2
	v_add_f32_e32 v165, v145, v165
	v_add_f32_e32 v166, v146, v166
	v_add_f32_e32 v167, v147, v167
	v_add_f32_e32 v2, v148, v2
	v_add_f32_e32 v165, v149, v165
	v_add_f32_e32 v166, v150, v166
	v_add_f32_e32 v167, v151, v167
	v_add_f32_e32 v2, v152, v2
	v_add_f32_e32 v165, v153, v165
	v_add_f32_e32 v166, v154, v166
	v_add_f32_e32 v167, v155, v167
	v_add_f32_e32 v2, v156, v2
	v_add_f32_e32 v165, v157, v165
	v_add_f32_e32 v166, v158, v166
	v_add_f32_e32 v167, v159, v167
	v_add_f32_e32 v2, v2, v165
	v_add_f32_e32 v165, v166, v167
	v_add_f32_e32 v220, v2, v165
	v_mov_b32_e32 v221, v220
	v_cvt_pk_bf16_f32 v2, v3, v4
	v_cvt_pk_bf16_f32 v3, v5, v6
	v_cvt_pk_bf16_f32 v4, v7, v8
	v_cvt_pk_bf16_f32 v5, v9, v10
	v_cvt_pk_bf16_f32 v6, v11, v12
	v_cvt_pk_bf16_f32 v7, v13, v160
	v_cvt_pk_bf16_f32 v8, v161, v162
	v_cvt_pk_bf16_f32 v9, v163, v164
	v_cvt_pk_bf16_f32 v10, v144, v145
	v_cvt_pk_bf16_f32 v11, v146, v147
	v_cvt_pk_bf16_f32 v12, v148, v149
	v_cvt_pk_bf16_f32 v13, v150, v151
	v_cvt_pk_bf16_f32 v144, v152, v153
	v_cvt_pk_bf16_f32 v145, v154, v155
	v_cvt_pk_bf16_f32 v146, v156, v157
	v_cvt_pk_bf16_f32 v147, v158, v159
	s_nop 1
	v_permlane32_swap_b32_e32 v220, v221
	v_cmp_gt_f32_e32 vcc, 1.0, v15
	s_cbranch_vccz .LBB0_341
; __device__ __forceinline__ void pv_d0(f32x16* o, int vb, bf16x8 pa0, bf16x8 pa1, bf16x8 pa2, bf16x8 pa3) {
;     ...
;   const s16x4 l0 = tr_read<v_rd_off(0, 0, 0)>(vb), h0 = tr_read<v_rd_off(0, 0, 1)>(vb);
;   const s16x4 l1 = tr_read<v_rd_off(0, 1, 0)>(vb), h1 = tr_read<v_rd_off(0, 1, 1)>(vb);
;   const s16x4 l2 = tr_read<v_rd_off(0, 2, 0)>(vb), h2 = tr_read<v_rd_off(0, 2, 1)>(vb);
;   const s16x4 l3 = tr_read<v_rd_off(0, 3, 0)>(vb), h3 = tr_read<v_rd_off(0, 3, 1)>(vb);
;   const s16x4 l4 = tr_read<v_rd_off(1, 0, 0)>(vb), h4 = tr_read<v_rd_off(1, 0, 1)>(vb);
;   asm volatile("s_waitcnt lgkmcnt(8)" ::: "memory"); SBAR();
;   o[0] = __builtin_amdgcn_mfma_f32_32x32x16_bf16(pa0, PK(l0, h0), o[0], 0, 0, 0);
;   const s16x4 l5 = tr_read<v_rd_off(1, 1, 0)>(vb), h5 = tr_read<v_rd_off(1, 1, 1)>(vb);
;   asm volatile("s_waitcnt lgkmcnt(8)" ::: "memory"); SBAR();
;   o[0] = __builtin_amdgcn_mfma_f32_32x32x16_bf16(pa1, PK(l1, h1), o[0], 0, 0, 0);
;   const s16x4 l6 = tr_read<v_rd_off(1, 2, 0)>(vb), h6 = tr_read<v_rd_off(1, 2, 1)>(vb);
;   asm volatile("s_waitcnt lgkmcnt(8)" ::: "memory"); SBAR();
;   o[0] = __builtin_amdgcn_mfma_f32_32x32x16_bf16(pa2, PK(l2, h2), o[0], 0, 0, 0);
;   const s16x4 l7 = tr_read<v_rd_off(1, 3, 0)>(vb), h7 = tr_read<v_rd_off(1, 3, 1)>(vb);
;   asm volatile("s_waitcnt lgkmcnt(8)" ::: "memory"); SBAR();
;   o[0] = __builtin_amdgcn_mfma_f32_32x32x16_bf16(pa3, PK(l3, h3), o[0], 0, 0, 0);
;   const s16x4 l8 = tr_read<v_rd_off(2, 0, 0)>(vb), h8 = tr_read<v_rd_off(2, 0, 1)>(vb);
;   asm volatile("s_waitcnt lgkmcnt(8)" ::: "memory"); SBAR();
;   o[1] = __builtin_amdgcn_mfma_f32_32x32x16_bf16(pa0, PK(l4, h4), o[1], 0, 0, 0);
;   const s16x4 l9 = tr_read<v_rd_off(2, 1, 0)>(vb), h9 = tr_read<v_rd_off(2, 1, 1)>(vb);
;   asm volatile("s_waitcnt lgkmcnt(8)" ::: "memory"); SBAR();
;   o[1] = __builtin_amdgcn_mfma_f32_32x32x16_bf16(pa1, PK(l5, h5), o[1], 0, 0, 0);
;   const s16x4 l10 = tr_read<v_rd_off(2, 2, 0)>(vb), h10 = tr_read<v_rd_off(2, 2, 1)>(vb);
;   asm volatile("s_waitcnt lgkmcnt(8)" ::: "memory"); SBAR();
;   o[1] = __builtin_amdgcn_mfma_f32_32x32x16_bf16(pa2, PK(l6, h6), o[1], 0, 0, 0);
;   const s16x4 l11 = tr_read<v_rd_off(2, 3, 0)>(vb), h11 = tr_read<v_rd_off(2, 3, 1)>(vb);
;   asm volatile("s_waitcnt lgkmcnt(8)" ::: "memory"); SBAR();
;   o[1] = __builtin_amdgcn_mfma_f32_32x32x16_bf16(pa3, PK(l7, h7), o[1], 0, 0, 0);
	s_and_saveexec_b64 s[8:9], s[4:5]
	ds_write_b32 v215, v15
	s_or_b64 exec, exec, s[8:9]
	s_waitcnt lgkmcnt(0)
	ds_read_b128 v[148:151], v216 offset:96
	ds_read_b128 v[152:155], v216 offset:64
	ds_read_b128 v[156:159], v216 offset:32
	ds_read_b128 v[160:163], v216
	s_waitcnt lgkmcnt(3)
	v_pk_mul_f32 v[142:143], v[142:143], v[150:151]
	s_waitcnt lgkmcnt(2)
	v_pk_mul_f32 v[138:139], v[138:139], v[154:155]
	s_waitcnt lgkmcnt(1)
	v_pk_mul_f32 v[134:135], v[134:135], v[158:159]
	s_waitcnt lgkmcnt(0)
	v_pk_mul_f32 v[130:131], v[130:131], v[162:163]
	v_pk_mul_f32 v[140:141], v[140:141], v[148:149]
	v_pk_mul_f32 v[136:137], v[136:137], v[152:153]
	v_pk_mul_f32 v[132:133], v[132:133], v[156:157]
	v_pk_mul_f32 v[128:129], v[128:129], v[160:161]
	v_pk_mul_f32 v[110:111], v[110:111], v[150:151]
	v_pk_mul_f32 v[106:107], v[106:107], v[154:155]
	v_pk_mul_f32 v[102:103], v[102:103], v[158:159]
	v_pk_mul_f32 v[98:99], v[98:99], v[162:163]
	v_pk_mul_f32 v[108:109], v[108:109], v[148:149]
	v_pk_mul_f32 v[104:105], v[104:105], v[152:153]
	v_pk_mul_f32 v[100:101], v[100:101], v[156:157]
	v_pk_mul_f32 v[96:97], v[96:97], v[160:161]
	v_pk_mul_f32 v[62:63], v[62:63], v[150:151]
	v_pk_mul_f32 v[58:59], v[58:59], v[154:155]
	v_pk_mul_f32 v[54:55], v[54:55], v[158:159]
	v_pk_mul_f32 v[50:51], v[50:51], v[162:163]
	v_pk_mul_f32 v[60:61], v[60:61], v[148:149]
	v_pk_mul_f32 v[56:57], v[56:57], v[152:153]
	v_pk_mul_f32 v[52:53], v[52:53], v[156:157]
	v_pk_mul_f32 v[48:49], v[48:49], v[160:161]
	v_pk_mul_f32 v[94:95], v[94:95], v[150:151]
	v_pk_mul_f32 v[90:91], v[90:91], v[154:155]
	v_pk_mul_f32 v[86:87], v[86:87], v[158:159]
	v_pk_mul_f32 v[82:83], v[82:83], v[162:163]
	v_pk_mul_f32 v[92:93], v[92:93], v[148:149]
	v_pk_mul_f32 v[88:89], v[88:89], v[152:153]
	v_pk_mul_f32 v[84:85], v[84:85], v[156:157]
	v_pk_mul_f32 v[80:81], v[80:81], v[160:161]
.LBB0_341:
	v_add_u32_e32 v222, s64, v214
	ds_read_b64_tr_b16 v[148:149], v222 offset:0
	ds_read_b64_tr_b16 v[150:151], v222 offset:0x800
	ds_read_b64_tr_b16 v[152:153], v222 offset:0x1000
	ds_read_b64_tr_b16 v[154:155], v222 offset:0x1800
	ds_read_b64_tr_b16 v[156:157], v222 offset:0x2000
	ds_read_b64_tr_b16 v[158:159], v222 offset:0x2800
	ds_read_b64_tr_b16 v[160:161], v222 offset:0x3000
	ds_read_b64_tr_b16 v[162:163], v222 offset:0x3800
	ds_read_b64_tr_b16 v[164:165], v222 offset:0x200
	ds_read_b64_tr_b16 v[166:167], v222 offset:0xa00
	s_waitcnt lgkmcnt(8)
	s_nop 0
	v_mfma_f32_32x32x16_bf16 v[128:143], v[2:5], v[148:151], v[128:143]
	ds_read_b64_tr_b16 v[148:149], v222 offset:0x1200
	ds_read_b64_tr_b16 v[150:151], v222 offset:0x1a00
	s_waitcnt lgkmcnt(8)
	v_mfma_f32_32x32x16_bf16 v[128:143], v[6:9], v[152:155], v[128:143]
	ds_read_b64_tr_b16 v[152:153], v222 offset:0x2200
	ds_read_b64_tr_b16 v[154:155], v222 offset:0x2a00
	s_waitcnt lgkmcnt(8)
	v_mfma_f32_32x32x16_bf16 v[128:143], v[10:13], v[156:159], v[128:143]
	ds_read_b64_tr_b16 v[156:157], v222 offset:0x3200
	ds_read_b64_tr_b16 v[158:159], v222 offset:0x3a00
	s_waitcnt lgkmcnt(8)
	v_mfma_f32_32x32x16_bf16 v[128:143], v[144:147], v[160:163], v[128:143]
	ds_read_b64_tr_b16 v[160:161], v222 offset:0x400
	ds_read_b64_tr_b16 v[162:163], v222 offset:0xc00
	s_waitcnt lgkmcnt(8)
	v_mfma_f32_32x32x16_bf16 v[96:111], v[2:5], v[164:167], v[96:111]
	ds_read_b64_tr_b16 v[164:165], v222 offset:0x1400
	ds_read_b64_tr_b16 v[166:167], v222 offset:0x1c00
	s_waitcnt lgkmcnt(8)
	v_mfma_f32_32x32x16_bf16 v[96:111], v[6:9], v[148:151], v[96:111]
	ds_read_b64_tr_b16 v[148:149], v222 offset:0x2400
	ds_read_b64_tr_b16 v[150:151], v222 offset:0x2c00
	s_waitcnt lgkmcnt(8)
	v_mfma_f32_32x32x16_bf16 v[96:111], v[10:13], v[152:155], v[96:111]
	ds_read_b64_tr_b16 v[152:153], v222 offset:0x3400
	ds_read_b64_tr_b16 v[154:155], v222 offset:0x3c00
	s_waitcnt lgkmcnt(8)
	v_mfma_f32_32x32x16_bf16 v[96:111], v[144:147], v[156:159], v[96:111]
	ds_read_b64_tr_b16 v[156:157], v222 offset:0x600
	ds_read_b64_tr_b16 v[158:159], v222 offset:0xe00
	s_waitcnt lgkmcnt(8)
	v_mfma_f32_32x32x16_bf16 v[48:63], v[2:5], v[160:163], v[48:63]
	ds_read_b64_tr_b16 v[160:161], v222 offset:0x1600
	ds_read_b64_tr_b16 v[162:163], v222 offset:0x1e00
	s_waitcnt lgkmcnt(8)
	v_mfma_f32_32x32x16_bf16 v[48:63], v[6:9], v[164:167], v[48:63]
	ds_read_b64_tr_b16 v[164:165], v222 offset:0x2600
	ds_read_b64_tr_b16 v[166:167], v222 offset:0x2e00
	s_waitcnt lgkmcnt(8)
	v_mfma_f32_32x32x16_bf16 v[48:63], v[10:13], v[148:151], v[48:63]
	ds_read_b64_tr_b16 v[148:149], v222 offset:0x3600
	ds_read_b64_tr_b16 v[150:151], v222 offset:0x3e00
	s_waitcnt lgkmcnt(8)
	v_mfma_f32_32x32x16_bf16 v[48:63], v[144:147], v[152:155], v[48:63]
	s_waitcnt lgkmcnt(6)
	v_mfma_f32_32x32x16_bf16 v[80:95], v[2:5], v[156:159], v[80:95]
	s_waitcnt lgkmcnt(4)
	v_mfma_f32_32x32x16_bf16 v[80:95], v[6:9], v[160:163], v[80:95]
	s_waitcnt lgkmcnt(2)
	v_mfma_f32_32x32x16_bf16 v[80:95], v[10:13], v[164:167], v[80:95]
	s_waitcnt lgkmcnt(0)
	v_mfma_f32_32x32x16_bf16 v[80:95], v[144:147], v[148:151], v[80:95]
	v_xor_b32_e32 v10, 0x80, v226
	ds_read_b128 v[2:5], v10 offset:0
	ds_read_b128 v[6:9], v10 offset:0x2000
	ds_read_b128 v[10:13], v208 offset:0x1000
	v_xor_b32_e32 v144, 0xa0, v226
	ds_read_b128 v[242:245], v144 offset:0
	ds_read_b128 v[246:249], v144 offset:0x2000
	ds_read_b128 v[250:253], v208 offset:0x1400
	v_sub_f32_e32 v160, v227, v218
	v_mov_b32_e32 v161, v160
	v_mov_b64_e32 v[162:163], v[160:161]
	v_mov_b64_e32 v[164:165], v[160:161]
	v_mov_b64_e32 v[166:167], v[160:161]
	v_mov_b64_e32 v[168:169], v[160:161]
	v_mov_b64_e32 v[170:171], v[160:161]
	v_mov_b64_e32 v[172:173], v[160:161]
	v_mov_b64_e32 v[174:175], v[160:161]
	v_mov_b64_e32 v[144:145], v[160:161]
	v_mov_b64_e32 v[146:147], v[160:161]
	v_mov_b64_e32 v[148:149], v[160:161]
	v_mov_b64_e32 v[150:151], v[160:161]
	v_mov_b64_e32 v[152:153], v[160:161]
	v_mov_b64_e32 v[154:155], v[160:161]
	v_mov_b64_e32 v[156:157], v[160:161]
	v_mov_b64_e32 v[158:159], v[160:161]
	s_waitcnt lgkmcnt(3)
	s_nop 0
	v_mfma_f32_32x32x16_bf16 v[160:175], v[2:5], v[10:13], v[160:175]
	v_mfma_f32_32x32x16_bf16 v[144:159], v[6:9], v[10:13], v[144:159]
	v_xor_b32_e32 v10, 0xc0, v226
	ds_read_b128 v[2:5], v10 offset:0
	ds_read_b128 v[6:9], v10 offset:0x2000
	ds_read_b128 v[10:13], v208 offset:0x1800
	s_waitcnt lgkmcnt(3)
	v_mfma_f32_32x32x16_bf16 v[160:175], v[242:245], v[250:253], v[160:175]
	v_xor_b32_e32 v192, 0xe0, v226
	ds_read_b128 v[242:245], v192 offset:0
	v_mfma_f32_32x32x16_bf16 v[144:159], v[246:249], v[250:253], v[144:159]
	ds_read_b128 v[246:249], v192 offset:0x2000
	ds_read_b128 v[250:253], v208 offset:0x1c00
	s_waitcnt lgkmcnt(3)
	v_mfma_f32_32x32x16_bf16 v[160:175], v[2:5], v[10:13], v[160:175]
	s_waitcnt lgkmcnt(0)
	v_mfma_f32_32x32x16_bf16 v[144:159], v[6:9], v[10:13], v[144:159]
	v_mfma_f32_32x32x16_bf16 v[160:175], v[242:245], v[250:253], v[160:175]
	v_mfma_f32_32x32x16_bf16 v[144:159], v[246:249], v[250:253], v[144:159]
	s_and_b64 vcc, exec, s[6:7]
	s_cbranch_vccnz .LBB0_343
; #define SBAR() __builtin_amdgcn_sched_barrier(0)
; __device__ __forceinline__ void softmax_tile(f32x16& p0, f32x16& p1, float& m, float& l, float& alpha, float cb, bf16x8& pa0, bf16x8& pa1, bf16x8& pa2, bf16x8& pa3) {
;   float mx_[4] = {p0[0], p0[1], p0[2], p0[3]};
; #pragma unroll
;   for (int r = 4; r < 16; ++r) mx_[r & 3] = fmaxf(mx_[r & 3], p0[r]);
; #pragma unroll
;   for (int r = 0; r < 16; ++r) mx_[r & 3] = fmaxf(mx_[r & 3], p1[r]);
;   float pmax = fmaxf(fmaxf(mx_[0], mx_[1]), fmaxf(mx_[2], mx_[3]));
;   { auto rr = __builtin_amdgcn_permlane32_swap(__float_as_uint(pmax), __float_as_uint(pmax), false, false);
;     pmax = fmaxf(__uint_as_float(rr[0]), __uint_as_float(rr[1])); }
;   pmax += cb;
;   float mn;
;   if (__builtin_expect(__all(pmax - m <= THR2), 1)) { mn = m; alpha = 1.f; }
;   else { mn = fmaxf(m, pmax); alpha = __builtin_amdgcn_exp2f(m - mn); m = mn; }
;   const float off = cb - mn;
; #pragma unroll
;   for (int r = 0; r < 16; ++r) p0[r] = __builtin_amdgcn_exp2f(p0[r] + off);
; #pragma unroll
;   for (int r = 0; r < 16; ++r) p1[r] = __builtin_amdgcn_exp2f(p1[r] + off);
;   float sm_[4] = {p0[0], p0[1], p0[2], p0[3]};
; #pragma unroll
;   for (int r = 4; r < 16; ++r) sm_[r & 3] += p0[r];
; #pragma unroll
;   for (int r = 0; r < 16; ++r) sm_[r & 3] += p1[r];
;   float ps = (sm_[0] + sm_[1]) + (sm_[2] + sm_[3]);
;   { auto rr = __builtin_amdgcn_permlane32_swap(__float_as_uint(ps), __float_as_uint(ps), false, false);
;     ps = __uint_as_float(rr[0]) + __uint_as_float(rr[1]); }
;   l = l * alpha + ps;
;     ...
;   PK4(p0, 0, pa0); PK4(p0, 8, pa1); PK4(p1, 0, pa2); PK4(p1, 8, pa3);
;     ...
; }
; __device__ __forceinline__ void attn_unit_A2(const bf16_t* __restrict__ Qb, int ldq, const bf16_t* __restrict__ Kh, int ldk, const bf16_t* __restrict__ Vh, int ldv, int nkeys, int q0, ...
;     ...
;     if (nearb) {
; #pragma unroll
;       for (int r = 0; r < 8; ++r) { s0[r] += tb_[(r & 3) + 8 * (r >> 2)]; s1[r] += tb_[32 + (r & 3) + 8 * (r >> 2)]; }
;       SBAR();
; #pragma unroll
;       for (int r = 8; r < 16; ++r) { s0[r] += tb_[(r & 3) + 8 * (r >> 2)]; s1[r] += tb_[32 + (r & 3) + 8 * (r >> 2)]; } }
;     SBAR();
;     softmax_tile(s0, s1, m1, l1, al1, cb, pa0, pa1, pa2, pa3);
;     RESC2(ob, sl1, al1);
	ds_read2_b32 v[2:3], v223 offset1:1
	ds_read2_b32 v[4:5], v234 offset1:1
	ds_read2_b32 v[6:7], v235 offset1:1
	ds_read2_b32 v[8:9], v236 offset1:1
	ds_read2_b32 v[10:11], v237 offset1:1
	ds_read2_b32 v[12:13], v238 offset1:1
	ds_read2_b32 v[192:193], v239 offset1:1
	ds_read2_b32 v[194:195], v240 offset1:1
	ds_read2_b32 v[202:203], v228 offset1:1
	ds_read2_b32 v[204:205], v229 offset1:1
	ds_read2_b32 v[228:229], v230 offset1:1
	ds_read2_b32 v[230:231], v231 offset1:1
	ds_read2_b32 v[234:235], v232 offset1:1
	ds_read2_b32 v[232:233], v233 offset1:1
	s_waitcnt lgkmcnt(9)
	v_add_f32_e32 v164, v164, v10
	v_add_f32_e32 v165, v165, v11
	v_add_f32_e32 v162, v162, v6
	v_add_f32_e32 v163, v163, v7
	ds_read2_b32 v[6:7], v225 offset1:1
	ds_read2_b32 v[10:11], v224 offset1:1
	s_waitcnt lgkmcnt(9)
	v_add_f32_e32 v166, v166, v192
	v_add_f32_e32 v167, v167, v193
	s_waitcnt lgkmcnt(2)
	v_add_f32_e32 v174, v174, v232
	v_add_f32_e32 v175, v175, v233
	v_add_f32_e32 v172, v172, v234
	v_add_f32_e32 v173, v173, v235
	v_add_f32_e32 v170, v170, v228
	v_add_f32_e32 v171, v171, v229
	v_add_f32_e32 v168, v168, v202
	v_add_f32_e32 v169, v169, v203
	v_add_f32_e32 v160, v160, v2
	v_add_f32_e32 v161, v161, v3
	v_add_f32_e32 v150, v150, v194
	v_add_f32_e32 v151, v151, v195
	v_add_f32_e32 v148, v148, v12
	v_add_f32_e32 v149, v149, v13
	v_add_f32_e32 v146, v146, v8
	v_add_f32_e32 v147, v147, v9
	s_waitcnt lgkmcnt(1)
	v_add_f32_e32 v158, v158, v6
	v_add_f32_e32 v159, v159, v7
	s_waitcnt lgkmcnt(0)
	v_add_f32_e32 v156, v156, v10
	v_add_f32_e32 v157, v157, v11
	v_add_f32_e32 v154, v154, v230
	v_add_f32_e32 v155, v155, v231
	v_add_f32_e32 v152, v152, v204
	v_add_f32_e32 v153, v153, v205
	v_add_f32_e32 v144, v144, v4
	v_add_f32_e32 v145, v145, v5
.LBB0_343:
	s_nop 8
	v_max_f32_e32 v2, v160, v164
	v_max_f32_e32 v3, v161, v165
	v_max_f32_e32 v4, v163, v167
	v_max3_f32 v5, v162, v166, v170
	v_max3_f32 v4, v4, v171, v175
	v_max3_f32 v2, v2, v168, v172
	v_max3_f32 v3, v3, v169, v173
	v_max3_f32 v5, v5, v174, v146
	v_max3_f32 v4, v4, v147, v151
	v_max3_f32 v2, v2, v144, v148
	v_max3_f32 v3, v3, v145, v149
	v_max3_f32 v5, v5, v150, v154
	v_max3_f32 v4, v4, v155, v159
	v_max3_f32 v2, v2, v152, v156
	v_max3_f32 v3, v3, v153, v157
	v_max3_f32 v4, v5, v158, v4
	v_max3_f32 v2, v2, v3, v4
	v_cmp_ge_f32_e32 vcc, s48, v2
	s_cmp_eq_u64 vcc, exec
	s_cbranch_scc0 .Lmy_A_rare1
	v_mov_b32_e32 v223, 1.0
.Lmy_A_back1:
	v_exp_f32_e32 v8, v165
	v_exp_f32_e32 v9, v166
	v_exp_f32_e32 v165, v148
	v_exp_f32_e32 v166, v149
	v_exp_f32_e32 v150, v150
	v_exp_f32_e32 v151, v151
	v_exp_f32_e32 v152, v152
	v_exp_f32_e32 v153, v153
	v_exp_f32_e32 v3, v160
	v_exp_f32_e32 v4, v161
	v_exp_f32_e32 v5, v162
	v_exp_f32_e32 v6, v163
	v_exp_f32_e32 v7, v164
	v_exp_f32_e32 v10, v167
	v_exp_f32_e32 v154, v154
	v_exp_f32_e32 v11, v168
	v_exp_f32_e32 v12, v169
	v_exp_f32_e32 v13, v170
	v_exp_f32_e32 v160, v171
	v_exp_f32_e32 v155, v155
	v_exp_f32_e32 v161, v172
	v_exp_f32_e32 v162, v173
	v_exp_f32_e32 v163, v174
	v_exp_f32_e32 v164, v175
	v_exp_f32_e32 v156, v156
	v_exp_f32_e32 v144, v144
	v_exp_f32_e32 v145, v145
	v_exp_f32_e32 v146, v146
	v_exp_f32_e32 v147, v147
	v_exp_f32_e32 v157, v157
	v_exp_f32_e32 v158, v158
	v_exp_f32_e32 v159, v159
	v_add_f32_e32 v2, v7, v3
	v_add_f32_e32 v148, v8, v4
	v_add_f32_e32 v149, v9, v5
	v_add_f32_e32 v167, v10, v6
	v_add_f32_e32 v2, v11, v2
	v_add_f32_e32 v148, v12, v148
	v_add_f32_e32 v149, v13, v149
	v_add_f32_e32 v167, v160, v167
	v_add_f32_e32 v2, v161, v2
	v_add_f32_e32 v148, v162, v148
	v_add_f32_e32 v149, v163, v149
	v_add_f32_e32 v167, v164, v167
	v_add_f32_e32 v2, v144, v2
	v_add_f32_e32 v148, v145, v148
	v_add_f32_e32 v149, v146, v149
	v_add_f32_e32 v167, v147, v167
	v_add_f32_e32 v2, v165, v2
	v_add_f32_e32 v148, v166, v148
	v_add_f32_e32 v149, v150, v149
	v_add_f32_e32 v167, v151, v167
	v_add_f32_e32 v2, v152, v2
	v_add_f32_e32 v148, v153, v148
	v_add_f32_e32 v149, v154, v149
	v_add_f32_e32 v167, v155, v167
	v_add_f32_e32 v2, v156, v2
	v_add_f32_e32 v148, v157, v148
	v_add_f32_e32 v149, v158, v149
	v_add_f32_e32 v167, v159, v167
	v_add_f32_e32 v2, v2, v148
	v_add_f32_e32 v148, v149, v167
	v_add_f32_e32 v148, v2, v148
	v_mov_b32_e32 v149, v148
	v_cvt_pk_bf16_f32 v2, v3, v4
	v_cvt_pk_bf16_f32 v3, v5, v6
	v_cvt_pk_bf16_f32 v4, v7, v8
	v_cvt_pk_bf16_f32 v5, v9, v10
	v_cvt_pk_bf16_f32 v6, v11, v12
	v_cvt_pk_bf16_f32 v7, v13, v160
	v_cvt_pk_bf16_f32 v8, v161, v162
	v_cvt_pk_bf16_f32 v9, v163, v164
	v_cvt_pk_bf16_f32 v10, v144, v145
	v_cvt_pk_bf16_f32 v11, v146, v147
	v_cvt_pk_bf16_f32 v12, v165, v166
	v_cvt_pk_bf16_f32 v13, v150, v151
	v_cvt_pk_bf16_f32 v144, v152, v153
	v_cvt_pk_bf16_f32 v145, v154, v155
	v_cvt_pk_bf16_f32 v146, v156, v157
	v_cvt_pk_bf16_f32 v147, v158, v159
	s_nop 1
	v_permlane32_swap_b32_e32 v148, v149
	v_cmp_gt_f32_e32 vcc, 1.0, v223
	s_cbranch_vccz .LBB0_347
	s_and_saveexec_b64 s[6:7], s[4:5]
	ds_write_b32 v215, v223 offset:128
	s_or_b64 exec, exec, s[6:7]
	s_waitcnt lgkmcnt(0)
	ds_read_b128 v[150:153], v216 offset:224
	ds_read_b128 v[154:157], v216 offset:192
	ds_read_b128 v[158:161], v216 offset:160
	ds_read_b128 v[162:165], v216 offset:128
	s_waitcnt lgkmcnt(3)
	v_pk_mul_f32 v[126:127], v[126:127], v[152:153]
	s_waitcnt lgkmcnt(2)
	v_pk_mul_f32 v[122:123], v[122:123], v[156:157]
	s_waitcnt lgkmcnt(1)
	v_pk_mul_f32 v[118:119], v[118:119], v[160:161]
	s_waitcnt lgkmcnt(0)
	v_pk_mul_f32 v[114:115], v[114:115], v[164:165]
	v_pk_mul_f32 v[124:125], v[124:125], v[150:151]
	v_pk_mul_f32 v[120:121], v[120:121], v[154:155]
	v_pk_mul_f32 v[116:117], v[116:117], v[158:159]
	v_pk_mul_f32 v[112:113], v[112:113], v[162:163]
	v_pk_mul_f32 v[78:79], v[78:79], v[152:153]
	v_pk_mul_f32 v[74:75], v[74:75], v[156:157]
	v_pk_mul_f32 v[70:71], v[70:71], v[160:161]
	v_pk_mul_f32 v[66:67], v[66:67], v[164:165]
	v_pk_mul_f32 v[76:77], v[76:77], v[150:151]
	v_pk_mul_f32 v[72:73], v[72:73], v[154:155]
	v_pk_mul_f32 v[68:69], v[68:69], v[158:159]
	v_pk_mul_f32 v[64:65], v[64:65], v[162:163]
	v_pk_mul_f32 v[30:31], v[30:31], v[152:153]
	v_pk_mul_f32 v[26:27], v[26:27], v[156:157]
	v_pk_mul_f32 v[22:23], v[22:23], v[160:161]
	v_pk_mul_f32 v[18:19], v[18:19], v[164:165]
	v_pk_mul_f32 v[28:29], v[28:29], v[150:151]
	v_pk_mul_f32 v[24:25], v[24:25], v[154:155]
	v_pk_mul_f32 v[20:21], v[20:21], v[158:159]
	v_pk_mul_f32 v[16:17], v[16:17], v[162:163]
	v_pk_mul_f32 v[46:47], v[46:47], v[152:153]
	v_pk_mul_f32 v[42:43], v[42:43], v[156:157]
	v_pk_mul_f32 v[38:39], v[38:39], v[160:161]
	v_pk_mul_f32 v[34:35], v[34:35], v[164:165]
	v_pk_mul_f32 v[44:45], v[44:45], v[150:151]
	v_pk_mul_f32 v[40:41], v[40:41], v[154:155]
	v_pk_mul_f32 v[36:37], v[36:37], v[158:159]
	v_pk_mul_f32 v[32:33], v[32:33], v[162:163]

; __device__ __forceinline__ void softmax_tile(f32x16& p0, f32x16& p1, float& m, float& l, float& alpha, float cb, bf16x8& pa0, bf16x8& pa1, bf16x8& pa2, bf16x8& pa3) {
;     ...
;   float pmax = fmaxf(fmaxf(mx_[0], mx_[1]), fmaxf(mx_[2], mx_[3]));
;   { auto rr = __builtin_amdgcn_permlane32_swap(__float_as_uint(pmax), __float_as_uint(pmax), false, false);
;     pmax = fmaxf(__uint_as_float(rr[0]), __uint_as_float(rr[1])); }
;   pmax += cb;
;   float mn;
;   if (__builtin_expect(__all(pmax - m <= THR2), 1)) { mn = m; alpha = 1.f; }
;   else { mn = fmaxf(m, pmax); alpha = __builtin_amdgcn_exp2f(m - mn); m = mn; }
.Lmy_A_rare0:
	v_mov_b32_e32 v3, v2
	s_nop 1
	v_permlane32_swap_b32_e32 v2, v3
	v_max_f32_e32 v2, v2, v3
	v_max_f32_e32 v2, 0, v2
	v_exp_f32_e64 v15, -v2
	v_add_f32_e32 v0, v0, v2
	v_sub_f32_e32 v160, v160, v2
	v_sub_f32_e32 v161, v161, v2
	v_sub_f32_e32 v162, v162, v2
	v_sub_f32_e32 v163, v163, v2
	v_sub_f32_e32 v164, v164, v2
	v_sub_f32_e32 v165, v165, v2
	v_sub_f32_e32 v166, v166, v2
	v_sub_f32_e32 v167, v167, v2
	v_sub_f32_e32 v168, v168, v2
	v_sub_f32_e32 v169, v169, v2
	v_sub_f32_e32 v170, v170, v2
	v_sub_f32_e32 v171, v171, v2
	v_sub_f32_e32 v172, v172, v2
	v_sub_f32_e32 v173, v173, v2
	v_sub_f32_e32 v174, v174, v2
	v_sub_f32_e32 v175, v175, v2
	v_sub_f32_e32 v144, v144, v2
	v_sub_f32_e32 v145, v145, v2
	v_sub_f32_e32 v146, v146, v2
	v_sub_f32_e32 v147, v147, v2
	v_sub_f32_e32 v148, v148, v2
	v_sub_f32_e32 v149, v149, v2
	v_sub_f32_e32 v150, v150, v2
	v_sub_f32_e32 v151, v151, v2
	v_sub_f32_e32 v152, v152, v2
	v_sub_f32_e32 v153, v153, v2
	v_sub_f32_e32 v154, v154, v2
	v_sub_f32_e32 v155, v155, v2
	v_sub_f32_e32 v156, v156, v2
	v_sub_f32_e32 v157, v157, v2
	v_sub_f32_e32 v158, v158, v2
	v_sub_f32_e32 v159, v159, v2
	s_branch .Lmy_A_back0
.Lmy_A_rare1:
	v_mov_b32_e32 v3, v2
	s_nop 1
	v_permlane32_swap_b32_e32 v2, v3
	v_max_f32_e32 v2, v2, v3
	v_max_f32_e32 v2, 0, v2
	v_exp_f32_e64 v223, -v2
	v_add_f32_e32 v218, v218, v2
	v_sub_f32_e32 v160, v160, v2
	v_sub_f32_e32 v161, v161, v2
	v_sub_f32_e32 v162, v162, v2
	v_sub_f32_e32 v163, v163, v2
	v_sub_f32_e32 v164, v164, v2
	v_sub_f32_e32 v165, v165, v2
	v_sub_f32_e32 v166, v166, v2
	v_sub_f32_e32 v167, v167, v2
	v_sub_f32_e32 v168, v168, v2
	v_sub_f32_e32 v169, v169, v2
	v_sub_f32_e32 v170, v170, v2
	v_sub_f32_e32 v171, v171, v2
	v_sub_f32_e32 v172, v172, v2
	v_sub_f32_e32 v173, v173, v2
	v_sub_f32_e32 v174, v174, v2
	v_sub_f32_e32 v175, v175, v2
	v_sub_f32_e32 v144, v144, v2
	v_sub_f32_e32 v145, v145, v2
	v_sub_f32_e32 v146, v146, v2
	v_sub_f32_e32 v147, v147, v2
	v_sub_f32_e32 v148, v148, v2
	v_sub_f32_e32 v149, v149, v2
	v_sub_f32_e32 v150, v150, v2
	v_sub_f32_e32 v151, v151, v2
	v_sub_f32_e32 v152, v152, v2
	v_sub_f32_e32 v153, v153, v2
	v_sub_f32_e32 v154, v154, v2
	v_sub_f32_e32 v155, v155, v2
	v_sub_f32_e32 v156, v156, v2
	v_sub_f32_e32 v157, v157, v2
	v_sub_f32_e32 v158, v158, v2
	v_sub_f32_e32 v159, v159, v2
	s_branch .Lmy_A_back1
